# plus: GLU phase spreads the f32 residual-input tile fetch over the K loop (one 16-lane touch load per wave per iteration), epilogue x loads cacheable
# baseline (speedup 1.0000x reference)
;     __device__ __forceinline__ size_t a_off(const Unit& u) const { return (size_t)u.pm * atile; }
;     __device__ __forceinline__ size_t b_off(const Unit& u) const { return (size_t)u.pn * btile; }
;     __device__ __forceinline__ size_t a_off(const Unit& u) const { return ((size_t)u.g * NROW + (size_t)u.pm * BM) * KA * 2; }
;     __device__ __forceinline__ size_t b_off(const Unit& u) const { return (size_t)u.g * btile; }
;     __device__ __forceinline__ size_t a_off(const Unit& u) const { return ((size_t)u.g * NROW + (size_t)u.pm * BM) * KA * 2; }
;     __device__ __forceinline__ size_t b_off(const Unit& u) const { return (size_t)u.g * btile; }
; #define PG8_STAGE(bufoff, gbase, voff) do { const __amdgpu_buffer_rsrc_t _r = __builtin_amdgcn_make_buffer_rsrc((void*)(gbase), (short)0, 0x7fffffff, 0x00020000); _Pragma("unroll") for (int _i = 0; _i < 2; ++_i) \
;         __builtin_amdgcn_raw_ptr_buffer_load_lds(_r, (LAS unsigned*)(lds + (bufoff) + ldsw + _i * 8192), 16, (int)(voff)[_i], 0, 0, 0); } while (0)
; #define PG8_LDA(dst, b, h) do { _Pragma("unroll") for (int m = 0; m < 4; ++m) _Pragma("unroll") for (int k = 0; k < 2; ++k) dst[m][k] = *(const LAS bf16x8*)(lds + PG8_SA(b, h) + aoff + m * 2048 + k * 1024); } while (0)
; #define PG8_WAIT_L(n) asm volatile("s_waitcnt lgkmcnt(" #n ")" ::: "memory")
;     ...
;         const char* nA = has_next ? (const char*)Ap + S.a_off(nxt) : cA; const char* nB = has_next ? (const char*)Btp + S.b_off(nxt) : cB;
;         for (int t = 0; t < nt; t += 2) {
;             const bool last = (t == nt - 2);
;             const char* a1 = cA + (size_t)(t + 1) * kstep;
;             const char* a2 = last ? nA : cA + (size_t)(t + 2) * kstep; const char* b2 = last ? nB : cB + (size_t)(t + 2) * kstep;
;             const char* a3 = a2 + kstep; const char* b3 = b2 + kstep;
;             PG8_LDB(B0, 0, 0); PG8_SCHED; PG8_LDA(At, 0, 0); PG8_STAGE(PG8_SA(1, 1), a1 + hstepA, voffA);
;             PG8_WAIT_L(8); PG8_BAR; PG8_WAIT_L(0); PG8_MMA(0, 0, At, B0); PG8_BAR; PG8_SCHED;
;             PG8_LDB(B1, 0, 1); PG8_STAGE(PG8_SB(0, 0), b2, voffB);
;             PG8_BAR; PG8_WAIT_L(0); PG8_MMA(0, 1, At, B1); PG8_BAR;
;             PG8_LDA(At, 0, 1); PG8_STAGE(PG8_SA(0, 0), a2, voffA);
;             PG8_BAR; PG8_WAIT_L(0); PG8_MMA(1, 0, At, B0); PG8_BAR; PG8_SCHED;
;             PG8_STAGE(PG8_SB(0, 1), b2 + hstepB, voffB);
.LBB0_625:
	s_ashr_i32 s97, s96, 31
	s_lshl_b64 s[8:9], s[96:97], 19
	s_add_u32 s68, s40, s8
	s_addc_u32 s69, s41, s9
	s_ashr_i32 s95, s94, 31
	s_lshl_b64 s[8:9], s[94:95], 19
	s_add_u32 s12, s3, s8
	v_cmp_lt_i64_e64 s[0:1], s[0:1], v[184:185]
	s_addc_u32 s13, s87, s9
	s_andn2_b64 vcc, exec, s[36:37]
	s_waitcnt lgkmcnt(0)
	s_cbranch_vccnz .Lkzero_627
	s_and_b64 s[0:1], s[0:1], exec
	s_cselect_b32 s0, s69, s27
	s_cselect_b32 s1, s68, s26
	s_cselect_b32 s47, s13, s25
	s_cselect_b32 s51, s12, s24
	s_add_u32 s89, s26, 0x100
	s_addc_u32 s90, s27, 0
	s_add_u32 s91, s24, 0x100
	s_mov_b64 s[44:45], s[36:37]
	s_addc_u32 s92, s25, 0
	s_mov_b32 s8, 0
	v_readlane_b32 s98, v252, 6
	v_readlane_b32 s99, v252, 7
	v_lshrrev_b32_e32 v226, 4, v232
	v_and_b32_e32 v226, 0x1c, v226
	v_bfe_u32 v227, v232, 2, 2
	v_or_b32_e32 v226, v226, v227
	v_lshl_add_u32 v226, s66, 8, v226
	v_lshlrev_b32_e32 v226, 12, v226
	v_and_b32_e32 v227, 3, v232
	v_lshl_add_u32 v226, v227, 7, v226
	v_lshl_add_u32 v230, s64, 9, v226
	v_mov_b32_e32 v231, 0
	v_mov_b32_e32 v228, 0x20000
	v_mov_b32_e32 v229, 0
	v_lshl_add_u64 v[226:227], v[230:231], 0, s[98:99]
	ds_read_b128 v[128:131], v212
	ds_read_b128 v[132:135], v212 offset:1024
	ds_read_b128 v[136:139], v212 offset:2048
	ds_read_b128 v[140:143], v212 offset:3072
	s_add_i32 s16, s8, 2
	s_cmp_eq_u32 s82, s8
	s_cselect_b32 s36, s1, s89
	s_cselect_b32 s23, s0, s90
	s_cselect_b32 s22, s47, s92
	s_cselect_b32 s28, s51, s91
	s_add_u32 s24, s36, 0x80
	s_addc_u32 s17, s23, 0
	s_add_u32 s8, s89, s18
	s_addc_u32 s9, s90, s19
	s_add_u32 s8, s8, 0xffffff80
	s_addc_u32 s9, s9, -1
	s_and_b32 s9, s9, 0xffff
	s_mov_b32 m0, s83
	ds_read_b128 v[144:147], v213
	ds_read_b128 v[148:151], v213 offset:1024
	ds_read_b128 v[152:155], v213 offset:2048
	ds_read_b128 v[156:159], v213 offset:3072
	ds_read_b128 v[160:163], v213 offset:4096
	ds_read_b128 v[164:167], v213 offset:5120
	ds_read_b128 v[168:171], v213 offset:6144
	ds_read_b128 v[172:175], v213 offset:7168
	buffer_load_dwordx4 v206, s[8:11], 0 offen lds
	s_mov_b32 m0, s84
	s_nop 0
	buffer_load_dwordx4 v208, s[8:11], 0 offen lds
	s_waitcnt lgkmcnt(8)
	s_barrier
	s_waitcnt lgkmcnt(0)
	s_setprio 1
	s_waitcnt lgkmcnt(7)
	v_mfma_f32_16x16x32_bf16 v[112:115], v[128:131], v[144:147], 0
	v_mfma_f32_16x16x32_bf16 v[116:119], v[136:139], v[144:147], 0
	s_waitcnt lgkmcnt(5)
	v_mfma_f32_16x16x32_bf16 v[100:103], v[128:131], v[152:155], 0
	v_mfma_f32_16x16x32_bf16 v[96:99], v[136:139], v[152:155], 0
	s_waitcnt lgkmcnt(3)
	v_mfma_f32_16x16x32_bf16 v[84:87], v[128:131], v[160:163], 0
	v_mfma_f32_16x16x32_bf16 v[80:83], v[136:139], v[160:163], 0
	s_waitcnt lgkmcnt(1)
	v_mfma_f32_16x16x32_bf16 v[68:71], v[128:131], v[168:171], 0
	v_mfma_f32_16x16x32_bf16 v[64:67], v[136:139], v[168:171], 0
	v_mfma_f32_16x16x32_bf16 v[112:115], v[132:135], v[148:151], v[112:115]
	v_mfma_f32_16x16x32_bf16 v[116:119], v[140:143], v[148:151], v[116:119]
	v_mfma_f32_16x16x32_bf16 v[100:103], v[132:135], v[156:159], v[100:103]
	v_mfma_f32_16x16x32_bf16 v[96:99], v[140:143], v[156:159], v[96:99]
	v_mfma_f32_16x16x32_bf16 v[84:87], v[132:135], v[164:167], v[84:87]
	v_mfma_f32_16x16x32_bf16 v[80:83], v[140:143], v[164:167], v[80:83]
	s_waitcnt lgkmcnt(0)
	v_mfma_f32_16x16x32_bf16 v[68:71], v[132:135], v[172:175], v[68:71]
	v_mfma_f32_16x16x32_bf16 v[64:67], v[140:143], v[172:175], v[64:67]
	s_setprio 0
	s_barrier
	s_and_b32 s29, s22, 0xffff
	s_mov_b32 s30, s10
	s_mov_b32 s31, s11
	s_mov_b32 m0, s15
	ds_read_b128 v[176:179], v214
	ds_read_b128 v[180:183], v214 offset:1024
	ds_read_b128 v[188:191], v214 offset:2048
	ds_read_b128 v[192:195], v214 offset:3072
	buffer_load_dwordx4 v207, s[28:31], 0 offen lds
	s_mov_b32 m0, s33
	s_nop 0
	buffer_load_dwordx4 v209, s[28:31], 0 offen lds
	s_barrier
	s_waitcnt lgkmcnt(0)
	s_setprio 1
	s_waitcnt lgkmcnt(3)
	v_mfma_f32_16x16x32_bf16 v[124:127], v[176:179], v[144:147], 0
	s_waitcnt lgkmcnt(1)
	v_mfma_f32_16x16x32_bf16 v[120:123], v[188:191], v[144:147], 0
	v_mfma_f32_16x16x32_bf16 v[108:111], v[176:179], v[152:155], 0
	v_mfma_f32_16x16x32_bf16 v[104:107], v[188:191], v[152:155], 0
	v_mfma_f32_16x16x32_bf16 v[92:95], v[176:179], v[160:163], 0
	v_mfma_f32_16x16x32_bf16 v[88:91], v[188:191], v[160:163], 0
	v_mfma_f32_16x16x32_bf16 v[76:79], v[176:179], v[168:171], 0
	v_mfma_f32_16x16x32_bf16 v[72:75], v[188:191], v[168:171], 0
	v_mfma_f32_16x16x32_bf16 v[124:127], v[180:183], v[148:151], v[124:127]
	s_waitcnt lgkmcnt(0)
	v_mfma_f32_16x16x32_bf16 v[120:123], v[192:195], v[148:151], v[120:123]
	v_mfma_f32_16x16x32_bf16 v[108:111], v[180:183], v[156:159], v[108:111]
	v_mfma_f32_16x16x32_bf16 v[104:107], v[192:195], v[156:159], v[104:107]
	v_mfma_f32_16x16x32_bf16 v[92:95], v[180:183], v[164:167], v[92:95]
	v_mfma_f32_16x16x32_bf16 v[88:91], v[192:195], v[164:167], v[88:91]
	v_mfma_f32_16x16x32_bf16 v[76:79], v[180:183], v[172:175], v[76:79]
	v_mfma_f32_16x16x32_bf16 v[72:75], v[192:195], v[172:175], v[72:75]
	s_setprio 0
	s_and_b32 s37, s23, 0xffff
	s_mov_b32 s38, s10
	s_mov_b32 s39, s11
	s_mov_b32 m0, s14
	s_barrier
	ds_read_b128 v[144:147], v213 offset:16384
	ds_read_b128 v[148:151], v213 offset:17408
	ds_read_b128 v[152:155], v213 offset:18432
	ds_read_b128 v[156:159], v213 offset:19456
	ds_read_b128 v[160:163], v213 offset:20480
	ds_read_b128 v[164:167], v213 offset:21504
	ds_read_b128 v[168:171], v213 offset:22528
	ds_read_b128 v[172:175], v213 offset:23552
	buffer_load_dwordx4 v206, s[36:39], 0 offen lds
	s_mov_b32 m0, s35
	s_nop 0
	buffer_load_dwordx4 v208, s[36:39], 0 offen lds
	s_barrier
; #define PG8_STAGE(bufoff, gbase, voff) do { const __amdgpu_buffer_rsrc_t _r = __builtin_amdgcn_make_buffer_rsrc((void*)(gbase), (short)0, 0x7fffffff, 0x00020000); _Pragma("unroll") for (int _i = 0; _i < 2; ++_i) \
;         __builtin_amdgcn_raw_ptr_buffer_load_lds(_r, (LAS unsigned*)(lds + (bufoff) + ldsw + _i * 8192), 16, (int)(voff)[_i], 0, 0, 0); } while (0)
; #define PG8_LDA(dst, b, h) do { _Pragma("unroll") for (int m = 0; m < 4; ++m) _Pragma("unroll") for (int k = 0; k < 2; ++k) dst[m][k] = *(const LAS bf16x8*)(lds + PG8_SA(b, h) + aoff + m * 2048 + k * 1024); } while (0)
; #define PG8_LDB(dst, b, h) do { _Pragma("unroll") for (int n = 0; n < 2; ++n) _Pragma("unroll") for (int k = 0; k < 2; ++k) dst[n][k] = *(const LAS bf16x8*)(lds + PG8_SB(b, h) + boff + n * 2048 + k * 1024); } while (0)
; #define PG8_MMA(ai, bj, At, Bt) do { __builtin_amdgcn_s_setprio(1); _Pragma("unroll") for (int k = 0; k < 2; ++k) _Pragma("unroll") for (int m = 0; m < 4; ++m) _Pragma("unroll") for (int n = 0; n < ((bj) == 1 ? NB1 : 2); ++n) \
;         acc[ai][bj][m][n] = __builtin_amdgcn_mfma_f32_16x16x32_bf16(Bt[n][k], At[m][k], acc[ai][bj][m][n], 0, 0, 0); __builtin_amdgcn_s_setprio(0); } while (0)
; #define PG8_WAIT_V(n) asm volatile("s_waitcnt vmcnt(" #n ")" ::: "memory")
; #define PG8_WAIT_L(n) asm volatile("s_waitcnt lgkmcnt(" #n ")" ::: "memory")
; #define PG8_BAR __builtin_amdgcn_s_barrier()
; #define PG8_SCHED __builtin_amdgcn_sched_barrier(0)
;     ...
;             PG8_STAGE(PG8_SB(0, 1), b2 + hstepB, voffB);
;             PG8_WAIT_V(6); PG8_BAR; PG8_MMA(1, 1, At, B1); PG8_BAR;
;             PG8_LDB(B0, 1, 0); PG8_SCHED; PG8_LDA(At, 1, 0); PG8_STAGE(PG8_SA(0, 1), a2 + hstepA, voffA);
;             PG8_WAIT_L(8); PG8_BAR; PG8_WAIT_L(0); PG8_MMA(0, 0, At, B0); PG8_BAR; PG8_SCHED;
	s_waitcnt lgkmcnt(0)
	s_setprio 1
	s_waitcnt lgkmcnt(7)
	v_mfma_f32_16x16x32_bf16 v[52:55], v[128:131], v[144:147], 0
	v_mfma_f32_16x16x32_bf16 v[48:51], v[136:139], v[144:147], 0
	s_waitcnt lgkmcnt(5)
	v_mfma_f32_16x16x32_bf16 v[36:39], v[128:131], v[152:155], 0
	v_mfma_f32_16x16x32_bf16 v[32:35], v[136:139], v[152:155], 0
	s_waitcnt lgkmcnt(3)
	v_mfma_f32_16x16x32_bf16 v[20:23], v[128:131], v[160:163], 0
	v_mfma_f32_16x16x32_bf16 v[16:19], v[136:139], v[160:163], 0
	s_waitcnt lgkmcnt(1)
	v_mfma_f32_16x16x32_bf16 v[4:7], v[128:131], v[168:171], 0
	v_mfma_f32_16x16x32_bf16 v[0:3], v[136:139], v[168:171], 0
	v_mfma_f32_16x16x32_bf16 v[52:55], v[132:135], v[148:151], v[52:55]
	v_mfma_f32_16x16x32_bf16 v[48:51], v[140:143], v[148:151], v[48:51]
	v_mfma_f32_16x16x32_bf16 v[36:39], v[132:135], v[156:159], v[36:39]
	v_mfma_f32_16x16x32_bf16 v[32:35], v[140:143], v[156:159], v[32:35]
	v_mfma_f32_16x16x32_bf16 v[20:23], v[132:135], v[164:167], v[20:23]
	v_mfma_f32_16x16x32_bf16 v[16:19], v[140:143], v[164:167], v[16:19]
	s_waitcnt lgkmcnt(0)
	v_mfma_f32_16x16x32_bf16 v[4:7], v[132:135], v[172:175], v[4:7]
	v_mfma_f32_16x16x32_bf16 v[0:3], v[140:143], v[172:175], v[0:3]
	s_setprio 0
	s_barrier
	s_add_u32 s8, s28, s42
	s_addc_u32 s93, s22, s43
	s_and_b32 s9, s93, 0xffff
	s_mov_b32 m0, s65
	s_nop 0
	buffer_load_dwordx4 v207, s[8:11], 0 offen lds
	s_mov_b32 m0, s67
	s_nop 0
	buffer_load_dwordx4 v209, s[8:11], 0 offen lds
	s_waitcnt vmcnt(6)
	s_mov_b32 exec_lo, 0xffff
	s_mov_b32 exec_hi, 0
	global_load_dword v230, v[226:227], off
	s_mov_b64 exec, -1
	v_lshl_add_u64 v[226:227], v[228:229], 0, v[226:227]
	s_barrier
	s_setprio 1
	v_mfma_f32_16x16x32_bf16 v[60:63], v[176:179], v[144:147], 0
	v_mfma_f32_16x16x32_bf16 v[56:59], v[188:191], v[144:147], 0
	v_mfma_f32_16x16x32_bf16 v[44:47], v[176:179], v[152:155], 0
	v_mfma_f32_16x16x32_bf16 v[40:43], v[188:191], v[152:155], 0
	v_mfma_f32_16x16x32_bf16 v[28:31], v[176:179], v[160:163], 0
	v_mfma_f32_16x16x32_bf16 v[24:27], v[188:191], v[160:163], 0
	v_mfma_f32_16x16x32_bf16 v[12:15], v[176:179], v[168:171], 0
	v_mfma_f32_16x16x32_bf16 v[8:11], v[188:191], v[168:171], 0
	v_mfma_f32_16x16x32_bf16 v[60:63], v[180:183], v[148:151], v[60:63]
	v_mfma_f32_16x16x32_bf16 v[56:59], v[192:195], v[148:151], v[56:59]
	v_mfma_f32_16x16x32_bf16 v[44:47], v[180:183], v[156:159], v[44:47]
	v_mfma_f32_16x16x32_bf16 v[40:43], v[192:195], v[156:159], v[40:43]
	v_mfma_f32_16x16x32_bf16 v[28:31], v[180:183], v[164:167], v[28:31]
	v_mfma_f32_16x16x32_bf16 v[24:27], v[192:195], v[164:167], v[24:27]
	v_mfma_f32_16x16x32_bf16 v[12:15], v[180:183], v[172:175], v[12:15]
	v_mfma_f32_16x16x32_bf16 v[8:11], v[192:195], v[172:175], v[8:11]
	s_setprio 0
	s_barrier
	s_branch .Lkmid_627
.LBB0_627:
	ds_read_b128 v[128:131], v212
	ds_read_b128 v[132:135], v212 offset:1024
	ds_read_b128 v[136:139], v212 offset:2048
	ds_read_b128 v[140:143], v212 offset:3072
	s_add_i32 s16, s8, 2
	s_cmp_eq_u32 s82, s8
	s_cselect_b32 s36, s1, s89
	s_cselect_b32 s23, s0, s90
	s_cselect_b32 s22, s47, s92
	s_cselect_b32 s28, s51, s91
	s_add_u32 s24, s36, 0x80
	s_addc_u32 s17, s23, 0
	s_add_u32 s8, s89, s18
	s_addc_u32 s9, s90, s19
	s_add_u32 s8, s8, 0xffffff80
	s_addc_u32 s9, s9, -1
	s_and_b32 s9, s9, 0xffff
	s_mov_b32 m0, s83
	ds_read_b128 v[144:147], v213
	ds_read_b128 v[148:151], v213 offset:1024
	ds_read_b128 v[152:155], v213 offset:2048
	ds_read_b128 v[156:159], v213 offset:3072
	ds_read_b128 v[160:163], v213 offset:4096
	ds_read_b128 v[164:167], v213 offset:5120
	ds_read_b128 v[168:171], v213 offset:6144
	ds_read_b128 v[172:175], v213 offset:7168
	buffer_load_dwordx4 v206, s[8:11], 0 offen lds
	s_mov_b32 m0, s84
	s_nop 0
	buffer_load_dwordx4 v208, s[8:11], 0 offen lds
	s_waitcnt lgkmcnt(8)
	s_barrier
	s_waitcnt lgkmcnt(0)
	s_setprio 1
	s_waitcnt lgkmcnt(7)
	v_mfma_f32_16x16x32_bf16 v[112:115], v[128:131], v[144:147], v[112:115]
	v_mfma_f32_16x16x32_bf16 v[116:119], v[136:139], v[144:147], v[116:119]
	s_waitcnt lgkmcnt(5)
	v_mfma_f32_16x16x32_bf16 v[100:103], v[128:131], v[152:155], v[100:103]
	v_mfma_f32_16x16x32_bf16 v[96:99], v[136:139], v[152:155], v[96:99]
	s_waitcnt lgkmcnt(3)
	v_mfma_f32_16x16x32_bf16 v[84:87], v[128:131], v[160:163], v[84:87]
	v_mfma_f32_16x16x32_bf16 v[80:83], v[136:139], v[160:163], v[80:83]
	s_waitcnt lgkmcnt(1)
	v_mfma_f32_16x16x32_bf16 v[68:71], v[128:131], v[168:171], v[68:71]
	v_mfma_f32_16x16x32_bf16 v[64:67], v[136:139], v[168:171], v[64:67]
	v_mfma_f32_16x16x32_bf16 v[112:115], v[132:135], v[148:151], v[112:115]
	v_mfma_f32_16x16x32_bf16 v[116:119], v[140:143], v[148:151], v[116:119]
	v_mfma_f32_16x16x32_bf16 v[100:103], v[132:135], v[156:159], v[100:103]
	v_mfma_f32_16x16x32_bf16 v[96:99], v[140:143], v[156:159], v[96:99]
	v_mfma_f32_16x16x32_bf16 v[84:87], v[132:135], v[164:167], v[84:87]
	v_mfma_f32_16x16x32_bf16 v[80:83], v[140:143], v[164:167], v[80:83]
	s_waitcnt lgkmcnt(0)
	v_mfma_f32_16x16x32_bf16 v[68:71], v[132:135], v[172:175], v[68:71]
	v_mfma_f32_16x16x32_bf16 v[64:67], v[140:143], v[172:175], v[64:67]
	s_setprio 0
	s_barrier
; #define PG8_STAGE(bufoff, gbase, voff) do { const __amdgpu_buffer_rsrc_t _r = __builtin_amdgcn_make_buffer_rsrc((void*)(gbase), (short)0, 0x7fffffff, 0x00020000); _Pragma("unroll") for (int _i = 0; _i < 2; ++_i) \
;         __builtin_amdgcn_raw_ptr_buffer_load_lds(_r, (LAS unsigned*)(lds + (bufoff) + ldsw + _i * 8192), 16, (int)(voff)[_i], 0, 0, 0); } while (0)
; #define PG8_LDA(dst, b, h) do { _Pragma("unroll") for (int m = 0; m < 4; ++m) _Pragma("unroll") for (int k = 0; k < 2; ++k) dst[m][k] = *(const LAS bf16x8*)(lds + PG8_SA(b, h) + aoff + m * 2048 + k * 1024); } while (0)
; #define PG8_LDB(dst, b, h) do { _Pragma("unroll") for (int n = 0; n < 2; ++n) _Pragma("unroll") for (int k = 0; k < 2; ++k) dst[n][k] = *(const LAS bf16x8*)(lds + PG8_SB(b, h) + boff + n * 2048 + k * 1024); } while (0)
; #define PG8_MMA(ai, bj, At, Bt) do { __builtin_amdgcn_s_setprio(1); _Pragma("unroll") for (int k = 0; k < 2; ++k) _Pragma("unroll") for (int m = 0; m < 4; ++m) _Pragma("unroll") for (int n = 0; n < ((bj) == 1 ? NB1 : 2); ++n) \
;         acc[ai][bj][m][n] = __builtin_amdgcn_mfma_f32_16x16x32_bf16(Bt[n][k], At[m][k], acc[ai][bj][m][n], 0, 0, 0); __builtin_amdgcn_s_setprio(0); } while (0)
; #define PG8_WAIT_V(n) asm volatile("s_waitcnt vmcnt(" #n ")" ::: "memory")
; #define PG8_WAIT_L(n) asm volatile("s_waitcnt lgkmcnt(" #n ")" ::: "memory")
;     ...
;             PG8_LDB(B1, 0, 1); PG8_STAGE(PG8_SB(0, 0), b2, voffB);
;             PG8_BAR; PG8_WAIT_L(0); PG8_MMA(0, 1, At, B1); PG8_BAR;
;             PG8_LDA(At, 0, 1); PG8_STAGE(PG8_SA(0, 0), a2, voffA);
;             PG8_BAR; PG8_WAIT_L(0); PG8_MMA(1, 0, At, B0); PG8_BAR; PG8_SCHED;
;             PG8_STAGE(PG8_SB(0, 1), b2 + hstepB, voffB);
;             PG8_WAIT_V(6); PG8_BAR; PG8_MMA(1, 1, At, B1); PG8_BAR;
;             PG8_LDB(B0, 1, 0); PG8_SCHED; PG8_LDA(At, 1, 0); PG8_STAGE(PG8_SA(0, 1), a2 + hstepA, voffA);
;             PG8_WAIT_L(8); PG8_BAR; PG8_WAIT_L(0); PG8_MMA(0, 0, At, B0); PG8_BAR; PG8_SCHED;
;             PG8_LDB(B1, 1, 1); PG8_STAGE(PG8_SB(1, 0), b3, voffB);
;             PG8_BAR; PG8_WAIT_L(0); PG8_MMA(0, 1, At, B1); PG8_BAR;
;             PG8_LDA(At, 1, 1); PG8_STAGE(PG8_SA(1, 0), a3, voffA);
;             PG8_BAR; PG8_WAIT_L(0); PG8_MMA(1, 0, At, B0); PG8_BAR; PG8_SCHED;
;             PG8_STAGE(PG8_SB(1, 1), b3 + hstepB, voffB);
;             PG8_WAIT_V(6); PG8_BAR; PG8_MMA(1, 1, At, B1); PG8_BAR;
	s_and_b32 s29, s22, 0xffff
	s_mov_b32 s30, s10
	s_mov_b32 s31, s11
	s_mov_b32 m0, s15
	ds_read_b128 v[176:179], v214
	ds_read_b128 v[180:183], v214 offset:1024
	ds_read_b128 v[188:191], v214 offset:2048
	ds_read_b128 v[192:195], v214 offset:3072
	buffer_load_dwordx4 v207, s[28:31], 0 offen lds
	s_mov_b32 m0, s33
	s_nop 0
	buffer_load_dwordx4 v209, s[28:31], 0 offen lds
	s_barrier
	s_waitcnt lgkmcnt(0)
	s_setprio 1
	s_waitcnt lgkmcnt(3)
	v_mfma_f32_16x16x32_bf16 v[124:127], v[176:179], v[144:147], v[124:127]
	s_waitcnt lgkmcnt(1)
	v_mfma_f32_16x16x32_bf16 v[120:123], v[188:191], v[144:147], v[120:123]
	v_mfma_f32_16x16x32_bf16 v[108:111], v[176:179], v[152:155], v[108:111]
	v_mfma_f32_16x16x32_bf16 v[104:107], v[188:191], v[152:155], v[104:107]
	v_mfma_f32_16x16x32_bf16 v[92:95], v[176:179], v[160:163], v[92:95]
	v_mfma_f32_16x16x32_bf16 v[88:91], v[188:191], v[160:163], v[88:91]
	v_mfma_f32_16x16x32_bf16 v[76:79], v[176:179], v[168:171], v[76:79]
	v_mfma_f32_16x16x32_bf16 v[72:75], v[188:191], v[168:171], v[72:75]
	v_mfma_f32_16x16x32_bf16 v[124:127], v[180:183], v[148:151], v[124:127]
	s_waitcnt lgkmcnt(0)
	v_mfma_f32_16x16x32_bf16 v[120:123], v[192:195], v[148:151], v[120:123]
	v_mfma_f32_16x16x32_bf16 v[108:111], v[180:183], v[156:159], v[108:111]
	v_mfma_f32_16x16x32_bf16 v[104:107], v[192:195], v[156:159], v[104:107]
	v_mfma_f32_16x16x32_bf16 v[92:95], v[180:183], v[164:167], v[92:95]
	v_mfma_f32_16x16x32_bf16 v[88:91], v[192:195], v[164:167], v[88:91]
	v_mfma_f32_16x16x32_bf16 v[76:79], v[180:183], v[172:175], v[76:79]
	v_mfma_f32_16x16x32_bf16 v[72:75], v[192:195], v[172:175], v[72:75]
	s_setprio 0
	s_and_b32 s37, s23, 0xffff
	s_mov_b32 s38, s10
	s_mov_b32 s39, s11
	s_mov_b32 m0, s14
	s_barrier
	ds_read_b128 v[144:147], v213 offset:16384
	ds_read_b128 v[148:151], v213 offset:17408
	ds_read_b128 v[152:155], v213 offset:18432
	ds_read_b128 v[156:159], v213 offset:19456
	ds_read_b128 v[160:163], v213 offset:20480
	ds_read_b128 v[164:167], v213 offset:21504
	ds_read_b128 v[168:171], v213 offset:22528
	ds_read_b128 v[172:175], v213 offset:23552
	buffer_load_dwordx4 v206, s[36:39], 0 offen lds
	s_mov_b32 m0, s35
	s_nop 0
	buffer_load_dwordx4 v208, s[36:39], 0 offen lds
	s_barrier
	s_waitcnt lgkmcnt(0)
	s_setprio 1
	s_waitcnt lgkmcnt(7)
	v_mfma_f32_16x16x32_bf16 v[52:55], v[128:131], v[144:147], v[52:55]
	v_mfma_f32_16x16x32_bf16 v[48:51], v[136:139], v[144:147], v[48:51]
	s_waitcnt lgkmcnt(5)
	v_mfma_f32_16x16x32_bf16 v[36:39], v[128:131], v[152:155], v[36:39]
	v_mfma_f32_16x16x32_bf16 v[32:35], v[136:139], v[152:155], v[32:35]
	s_waitcnt lgkmcnt(3)
	v_mfma_f32_16x16x32_bf16 v[20:23], v[128:131], v[160:163], v[20:23]
	v_mfma_f32_16x16x32_bf16 v[16:19], v[136:139], v[160:163], v[16:19]
	s_waitcnt lgkmcnt(1)
	v_mfma_f32_16x16x32_bf16 v[4:7], v[128:131], v[168:171], v[4:7]
	v_mfma_f32_16x16x32_bf16 v[0:3], v[136:139], v[168:171], v[0:3]
	v_mfma_f32_16x16x32_bf16 v[52:55], v[132:135], v[148:151], v[52:55]
	v_mfma_f32_16x16x32_bf16 v[48:51], v[140:143], v[148:151], v[48:51]
	v_mfma_f32_16x16x32_bf16 v[36:39], v[132:135], v[156:159], v[36:39]
	v_mfma_f32_16x16x32_bf16 v[32:35], v[140:143], v[156:159], v[32:35]
	v_mfma_f32_16x16x32_bf16 v[20:23], v[132:135], v[164:167], v[20:23]
	v_mfma_f32_16x16x32_bf16 v[16:19], v[140:143], v[164:167], v[16:19]
	s_waitcnt lgkmcnt(0)
	v_mfma_f32_16x16x32_bf16 v[4:7], v[132:135], v[172:175], v[4:7]
	v_mfma_f32_16x16x32_bf16 v[0:3], v[140:143], v[172:175], v[0:3]
	s_setprio 0
	s_barrier
	s_add_u32 s8, s28, s42
	s_addc_u32 s93, s22, s43
	s_and_b32 s9, s93, 0xffff
	s_mov_b32 m0, s65
	s_nop 0
	buffer_load_dwordx4 v207, s[8:11], 0 offen lds
	s_mov_b32 m0, s67
	s_nop 0
	buffer_load_dwordx4 v209, s[8:11], 0 offen lds
	s_waitcnt vmcnt(6)
	s_mov_b32 exec_lo, 0xffff
	s_mov_b32 exec_hi, 0
	global_load_dword v230, v[226:227], off
	s_mov_b64 exec, -1
	v_lshl_add_u64 v[226:227], v[228:229], 0, v[226:227]
	s_barrier
	s_setprio 1
	v_mfma_f32_16x16x32_bf16 v[60:63], v[176:179], v[144:147], v[60:63]
	v_mfma_f32_16x16x32_bf16 v[56:59], v[188:191], v[144:147], v[56:59]
	v_mfma_f32_16x16x32_bf16 v[44:47], v[176:179], v[152:155], v[44:47]
	v_mfma_f32_16x16x32_bf16 v[40:43], v[188:191], v[152:155], v[40:43]
	v_mfma_f32_16x16x32_bf16 v[28:31], v[176:179], v[160:163], v[28:31]
	v_mfma_f32_16x16x32_bf16 v[24:27], v[188:191], v[160:163], v[24:27]
	v_mfma_f32_16x16x32_bf16 v[12:15], v[176:179], v[168:171], v[12:15]
	v_mfma_f32_16x16x32_bf16 v[8:11], v[188:191], v[168:171], v[8:11]
	v_mfma_f32_16x16x32_bf16 v[60:63], v[180:183], v[148:151], v[60:63]
	v_mfma_f32_16x16x32_bf16 v[56:59], v[192:195], v[148:151], v[56:59]
	v_mfma_f32_16x16x32_bf16 v[44:47], v[180:183], v[156:159], v[44:47]
	v_mfma_f32_16x16x32_bf16 v[40:43], v[192:195], v[156:159], v[40:43]
	v_mfma_f32_16x16x32_bf16 v[28:31], v[180:183], v[164:167], v[28:31]
	v_mfma_f32_16x16x32_bf16 v[24:27], v[192:195], v[164:167], v[24:27]
	v_mfma_f32_16x16x32_bf16 v[12:15], v[180:183], v[172:175], v[12:15]
	v_mfma_f32_16x16x32_bf16 v[8:11], v[192:195], v[172:175], v[8:11]
	s_setprio 0
	s_barrier

; __device__ __forceinline__ float fast_sigmoid(float x) { return __builtin_amdgcn_rcpf(1.0f + __builtin_amdgcn_exp2f(x * -1.44269504f)); }
;     __device__ __forceinline__ void operator()(const Acc& acc, const Unit& u, int wr, int wc, int fr, int fq, LAS unsigned char* lds, f32x4 epar) const {
;         const int c0 = u.pn * 128 + wc * 32 + 8 * fq;
;         f32x4 xv[2][4][2];
; #pragma unroll
;         for (int ai = 0; ai < 2; ++ai)
; #pragma unroll
;             for (int m = 0; m < 4; ++m) { const int r = u.pm * BM + ai * HALF + wr * 64 + m * 16 + fr; const size_t off = (size_t)r * DM + c0;
;                 xv[ai][m][0] = __builtin_nontemporal_load((const f32x4*)(x + off)); xv[ai][m][1] = __builtin_nontemporal_load((const f32x4*)(x + off + 4)); }
; #pragma unroll
;         for (int ai = 0; ai < 2; ++ai)
; #pragma unroll
;             for (int m = 0; m < 4; ++m) { const int r = u.pm * BM + ai * HALF + wr * 64 + m * 16 + fr; const size_t off = (size_t)r * DM + c0;
;                 f32x4 v0 = xv[ai][m][0], v1 = xv[ai][m][1];
;                 const f32x4 za0 = acc[ai][0][m][0], za1 = acc[ai][0][m][1], zg0 = acc[ai][1][m][0], zg1 = acc[ai][1][m][1];
; #pragma unroll
;                 for (int j = 0; j < 4; ++j) { v0[j] += za0[j] * fast_sigmoid(zg0[j]); v1[j] += za1[j] * fast_sigmoid(zg1[j]); }
.LBB0_629:
	v_readlane_b32 s44, v252, 6
	v_readlane_b32 s45, v252, 7
	v_readlane_b32 s46, v252, 8
	v_readlane_b32 s47, v252, 9
	v_readlane_b32 s48, v252, 10
	v_readlane_b32 s49, v252, 11
	v_readlane_b32 s50, v252, 12
	v_readlane_b32 s51, v252, 13
	v_readlane_b32 s52, v252, 14
	v_readlane_b32 s53, v252, 15
	v_readlane_b32 s54, v252, 16
	v_readlane_b32 s55, v252, 17
	v_readlane_b32 s56, v252, 18
	v_readlane_b32 s57, v252, 19
	v_readlane_b32 s58, v252, 20
	v_readlane_b32 s59, v252, 21
	s_mov_b64 s[0:1], exec
	v_lshl_add_u32 v188, s66, 8, v210
	v_lshl_or_b32 v189, s64, 7, v211
	v_lshlrev_b32_e32 v190, 12, v188
	v_lshlrev_b32_e32 v191, 11, v188
	v_lshlrev_b32_e32 v192, 2, v188
	v_lshl_add_u32 v190, v189, 2, v190
	v_lshl_add_u32 v191, v189, 1, v191
	global_load_dwordx4 v[222:225], v190, s[44:45]
	global_load_dwordx4 v[218:221], v190, s[44:45] offset:16
	v_add_u32_e32 v193, 0x10000, v190
	global_load_dwordx4 v[180:183], v193, s[44:45]
	global_load_dwordx4 v[176:179], v193, s[44:45] offset:16
	v_add_u32_e32 v193, 0x20000, v190
	global_load_dwordx4 v[172:175], v193, s[44:45]
	global_load_dwordx4 v[168:171], v193, s[44:45] offset:16
	v_add_u32_e32 v193, 0x30000, v190
	global_load_dwordx4 v[164:167], v193, s[44:45]
	global_load_dwordx4 v[160:163], v193, s[44:45] offset:16
	v_add_u32_e32 v193, 0x80000, v190
	global_load_dwordx4 v[156:159], v193, s[44:45]
	global_load_dwordx4 v[152:155], v193, s[44:45] offset:16
	v_add_u32_e32 v193, 0x90000, v190
	global_load_dwordx4 v[148:151], v193, s[44:45]
	global_load_dwordx4 v[144:147], v193, s[44:45] offset:16
	v_add_u32_e32 v193, 0xa0000, v190
	global_load_dwordx4 v[140:143], v193, s[44:45]
	global_load_dwordx4 v[136:139], v193, s[44:45] offset:16
	v_add_u32_e32 v193, 0xb0000, v190
	global_load_dwordx4 v[132:135], v193, s[44:45]
	global_load_dwordx4 v[128:131], v193, s[44:45] offset:16
	v_mul_f32_e32 v124, 0xbfb8aa3b, v124
	v_mul_f32_e32 v125, 0xbfb8aa3b, v125
	v_mul_f32_e32 v126, 0xbfb8aa3b, v126
	v_mul_f32_e32 v127, 0xbfb8aa3b, v127
	v_mul_f32_e32 v120, 0xbfb8aa3b, v120
	v_mul_f32_e32 v121, 0xbfb8aa3b, v121
	v_mul_f32_e32 v122, 0xbfb8aa3b, v122
	v_mul_f32_e32 v123, 0xbfb8aa3b, v123
	v_exp_f32_e32 v124, v124
	v_exp_f32_e32 v125, v125
	v_exp_f32_e32 v126, v126
	v_exp_f32_e32 v127, v127
	v_exp_f32_e32 v120, v120
	v_exp_f32_e32 v121, v121
	v_exp_f32_e32 v122, v122
	v_exp_f32_e32 v123, v123
	v_add_f32_e32 v124, 1.0, v124
	v_add_f32_e32 v125, 1.0, v125
	v_add_f32_e32 v126, 1.0, v126
	v_add_f32_e32 v127, 1.0, v127
	v_add_f32_e32 v120, 1.0, v120
	v_add_f32_e32 v121, 1.0, v121
	v_add_f32_e32 v122, 1.0, v122
	v_add_f32_e32 v123, 1.0, v123
	v_rcp_f32_e32 v124, v124
	v_rcp_f32_e32 v125, v125
	v_rcp_f32_e32 v126, v126
	v_rcp_f32_e32 v127, v127
	v_rcp_f32_e32 v120, v120
	v_rcp_f32_e32 v121, v121
	v_rcp_f32_e32 v122, v122
	v_rcp_f32_e32 v123, v123
	v_mul_f32_e32 v108, 0xbfb8aa3b, v108
	v_mul_f32_e32 v109, 0xbfb8aa3b, v109
	v_mul_f32_e32 v110, 0xbfb8aa3b, v110
	v_mul_f32_e32 v111, 0xbfb8aa3b, v111
	v_mul_f32_e32 v104, 0xbfb8aa3b, v104
	v_mul_f32_e32 v105, 0xbfb8aa3b, v105
	v_mul_f32_e32 v106, 0xbfb8aa3b, v106
	v_mul_f32_e32 v107, 0xbfb8aa3b, v107
	v_exp_f32_e32 v108, v108
	v_exp_f32_e32 v109, v109
	v_exp_f32_e32 v110, v110
	v_exp_f32_e32 v111, v111
	v_exp_f32_e32 v104, v104
	v_exp_f32_e32 v105, v105
	v_exp_f32_e32 v106, v106
	v_exp_f32_e32 v107, v107
	v_add_f32_e32 v108, 1.0, v108
	v_add_f32_e32 v109, 1.0, v109
	v_add_f32_e32 v110, 1.0, v110
	v_add_f32_e32 v111, 1.0, v111
	v_add_f32_e32 v104, 1.0, v104
	v_add_f32_e32 v105, 1.0, v105
	v_add_f32_e32 v106, 1.0, v106
	v_add_f32_e32 v107, 1.0, v107
	v_rcp_f32_e32 v108, v108
	v_rcp_f32_e32 v109, v109
	v_rcp_f32_e32 v110, v110
	v_rcp_f32_e32 v111, v111
	v_rcp_f32_e32 v104, v104
	v_rcp_f32_e32 v105, v105
	v_rcp_f32_e32 v106, v106
	v_rcp_f32_e32 v107, v107
	v_mul_f32_e32 v92, 0xbfb8aa3b, v92
	v_mul_f32_e32 v93, 0xbfb8aa3b, v93
	v_mul_f32_e32 v94, 0xbfb8aa3b, v94
	v_mul_f32_e32 v95, 0xbfb8aa3b, v95
	v_mul_f32_e32 v88, 0xbfb8aa3b, v88
	v_mul_f32_e32 v89, 0xbfb8aa3b, v89
	v_mul_f32_e32 v90, 0xbfb8aa3b, v90
	v_mul_f32_e32 v91, 0xbfb8aa3b, v91
	v_exp_f32_e32 v92, v92
	v_exp_f32_e32 v93, v93
	v_exp_f32_e32 v94, v94
	v_exp_f32_e32 v95, v95
	v_exp_f32_e32 v88, v88
	v_exp_f32_e32 v89, v89
	v_exp_f32_e32 v90, v90
	v_exp_f32_e32 v91, v91
	v_add_f32_e32 v92, 1.0, v92
	v_add_f32_e32 v93, 1.0, v93
	v_add_f32_e32 v94, 1.0, v94
	v_add_f32_e32 v95, 1.0, v95
	v_add_f32_e32 v88, 1.0, v88
	v_add_f32_e32 v89, 1.0, v89
	v_add_f32_e32 v90, 1.0, v90
	v_add_f32_e32 v91, 1.0, v91
	v_rcp_f32_e32 v92, v92
	v_rcp_f32_e32 v93, v93
	v_rcp_f32_e32 v94, v94
	v_rcp_f32_e32 v95, v95
	v_rcp_f32_e32 v88, v88
	v_rcp_f32_e32 v89, v89
	v_rcp_f32_e32 v90, v90
	v_rcp_f32_e32 v91, v91
	v_mul_f32_e32 v76, 0xbfb8aa3b, v76
	v_mul_f32_e32 v77, 0xbfb8aa3b, v77
	v_mul_f32_e32 v78, 0xbfb8aa3b, v78
	v_mul_f32_e32 v79, 0xbfb8aa3b, v79
	v_mul_f32_e32 v72, 0xbfb8aa3b, v72
	v_mul_f32_e32 v73, 0xbfb8aa3b, v73
	v_mul_f32_e32 v74, 0xbfb8aa3b, v74
	v_mul_f32_e32 v75, 0xbfb8aa3b, v75
	v_exp_f32_e32 v76, v76
	v_exp_f32_e32 v77, v77
	v_exp_f32_e32 v78, v78
	v_exp_f32_e32 v79, v79
	v_exp_f32_e32 v72, v72
	v_exp_f32_e32 v73, v73
	v_exp_f32_e32 v74, v74
	v_exp_f32_e32 v75, v75
	v_add_f32_e32 v76, 1.0, v76
	v_add_f32_e32 v77, 1.0, v77
	v_add_f32_e32 v78, 1.0, v78
	v_add_f32_e32 v79, 1.0, v79
	v_add_f32_e32 v72, 1.0, v72
	v_add_f32_e32 v73, 1.0, v73
	v_add_f32_e32 v74, 1.0, v74
	v_add_f32_e32 v75, 1.0, v75
	v_rcp_f32_e32 v76, v76
	v_rcp_f32_e32 v77, v77
	v_rcp_f32_e32 v78, v78
	v_rcp_f32_e32 v79, v79
	v_rcp_f32_e32 v72, v72
	v_rcp_f32_e32 v73, v73
	v_rcp_f32_e32 v74, v74
	v_rcp_f32_e32 v75, v75
	v_mul_f32_e32 v60, 0xbfb8aa3b, v60
; __device__ __forceinline__ unsigned cvt_pk_bf16(float lo, float hi) { unsigned r; asm volatile("v_cvt_pk_bf16_f32 %0, %1, %2" : "=v"(r) : "v"(lo), "v"(hi)); return r; }
; __device__ __forceinline__ float fast_sigmoid(float x) { return __builtin_amdgcn_rcpf(1.0f + __builtin_amdgcn_exp2f(x * -1.44269504f)); }
;     __device__ __forceinline__ void operator()(const Acc& acc, const Unit& u, int wr, int wc, int fr, int fq, LAS unsigned char* lds, f32x4 epar) const {
;     ...
;         for (int ai = 0; ai < 2; ++ai)
; #pragma unroll
;             for (int m = 0; m < 4; ++m) { const int r = u.pm * BM + ai * HALF + wr * 64 + m * 16 + fr; const size_t off = (size_t)r * DM + c0;
;                 f32x4 v0 = xv[ai][m][0], v1 = xv[ai][m][1];
;                 const f32x4 za0 = acc[ai][0][m][0], za1 = acc[ai][0][m][1], zg0 = acc[ai][1][m][0], zg1 = acc[ai][1][m][1];
; #pragma unroll
;                 for (int j = 0; j < 4; ++j) { v0[j] += za0[j] * fast_sigmoid(zg0[j]); v1[j] += za1[j] * fast_sigmoid(zg1[j]); }
;                 u32x4 w; w.x = cvt_pk_bf16(v0[0], v0[1]); w.y = cvt_pk_bf16(v0[2], v0[3]); w.z = cvt_pk_bf16(v1[0], v1[1]); w.w = cvt_pk_bf16(v1[2], v1[3]);
;                 *(u32x4*)(HB + off) = w;
;                 float s = (v0[0] * v0[0] + v0[1] * v0[1]) + (v0[2] * v0[2] + v0[3] * v0[3]) + (v1[0] * v1[0] + v1[1] * v1[1]) + (v1[2] * v1[2] + v1[3] * v1[3]);
;                 s += __shfl_xor(s, 16); s += __shfl_xor(s, 32);
;                 if (fq == 0) unsafeAtomicAdd(ssq + r, s); }
	v_mul_f32_e32 v61, 0xbfb8aa3b, v61
	v_mul_f32_e32 v62, 0xbfb8aa3b, v62
	v_mul_f32_e32 v63, 0xbfb8aa3b, v63
	v_mul_f32_e32 v56, 0xbfb8aa3b, v56
	v_mul_f32_e32 v57, 0xbfb8aa3b, v57
	v_mul_f32_e32 v58, 0xbfb8aa3b, v58
	v_mul_f32_e32 v59, 0xbfb8aa3b, v59
	v_exp_f32_e32 v60, v60
	v_exp_f32_e32 v61, v61
	v_exp_f32_e32 v62, v62
	v_exp_f32_e32 v63, v63
	v_exp_f32_e32 v56, v56
	v_exp_f32_e32 v57, v57
	v_exp_f32_e32 v58, v58
	v_exp_f32_e32 v59, v59
	v_add_f32_e32 v60, 1.0, v60
	v_add_f32_e32 v61, 1.0, v61
	v_add_f32_e32 v62, 1.0, v62
	v_add_f32_e32 v63, 1.0, v63
	v_add_f32_e32 v56, 1.0, v56
	v_add_f32_e32 v57, 1.0, v57
	v_add_f32_e32 v58, 1.0, v58
	v_add_f32_e32 v59, 1.0, v59
	v_rcp_f32_e32 v60, v60
	v_rcp_f32_e32 v61, v61
	v_rcp_f32_e32 v62, v62
	v_rcp_f32_e32 v63, v63
	v_rcp_f32_e32 v56, v56
	v_rcp_f32_e32 v57, v57
	v_rcp_f32_e32 v58, v58
	v_rcp_f32_e32 v59, v59
	v_mul_f32_e32 v44, 0xbfb8aa3b, v44
	v_mul_f32_e32 v45, 0xbfb8aa3b, v45
	v_mul_f32_e32 v46, 0xbfb8aa3b, v46
	v_mul_f32_e32 v47, 0xbfb8aa3b, v47
	v_mul_f32_e32 v40, 0xbfb8aa3b, v40
	v_mul_f32_e32 v41, 0xbfb8aa3b, v41
	v_mul_f32_e32 v42, 0xbfb8aa3b, v42
	v_mul_f32_e32 v43, 0xbfb8aa3b, v43
	v_exp_f32_e32 v44, v44
	v_exp_f32_e32 v45, v45
	v_exp_f32_e32 v46, v46
	v_exp_f32_e32 v47, v47
	v_exp_f32_e32 v40, v40
	v_exp_f32_e32 v41, v41
	v_exp_f32_e32 v42, v42
	v_exp_f32_e32 v43, v43
	v_add_f32_e32 v44, 1.0, v44
	v_add_f32_e32 v45, 1.0, v45
	v_add_f32_e32 v46, 1.0, v46
	v_add_f32_e32 v47, 1.0, v47
	v_add_f32_e32 v40, 1.0, v40
	v_add_f32_e32 v41, 1.0, v41
	v_add_f32_e32 v42, 1.0, v42
	v_add_f32_e32 v43, 1.0, v43
	v_rcp_f32_e32 v44, v44
	v_rcp_f32_e32 v45, v45
	v_rcp_f32_e32 v46, v46
	v_rcp_f32_e32 v47, v47
	v_rcp_f32_e32 v40, v40
	v_rcp_f32_e32 v41, v41
	v_rcp_f32_e32 v42, v42
	v_rcp_f32_e32 v43, v43
	v_mul_f32_e32 v28, 0xbfb8aa3b, v28
	v_mul_f32_e32 v29, 0xbfb8aa3b, v29
	v_mul_f32_e32 v30, 0xbfb8aa3b, v30
	v_mul_f32_e32 v31, 0xbfb8aa3b, v31
	v_mul_f32_e32 v24, 0xbfb8aa3b, v24
	v_mul_f32_e32 v25, 0xbfb8aa3b, v25
	v_mul_f32_e32 v26, 0xbfb8aa3b, v26
	v_mul_f32_e32 v27, 0xbfb8aa3b, v27
	v_exp_f32_e32 v28, v28
	v_exp_f32_e32 v29, v29
	v_exp_f32_e32 v30, v30
	v_exp_f32_e32 v31, v31
	v_exp_f32_e32 v24, v24
	v_exp_f32_e32 v25, v25
	v_exp_f32_e32 v26, v26
	v_exp_f32_e32 v27, v27
	v_add_f32_e32 v28, 1.0, v28
	v_add_f32_e32 v29, 1.0, v29
	v_add_f32_e32 v30, 1.0, v30
	v_add_f32_e32 v31, 1.0, v31
	v_add_f32_e32 v24, 1.0, v24
	v_add_f32_e32 v25, 1.0, v25
	v_add_f32_e32 v26, 1.0, v26
	v_add_f32_e32 v27, 1.0, v27
	v_rcp_f32_e32 v28, v28
	v_rcp_f32_e32 v29, v29
	v_rcp_f32_e32 v30, v30
	v_rcp_f32_e32 v31, v31
	v_rcp_f32_e32 v24, v24
	v_rcp_f32_e32 v25, v25
	v_rcp_f32_e32 v26, v26
	v_rcp_f32_e32 v27, v27
	v_mul_f32_e32 v12, 0xbfb8aa3b, v12
	v_mul_f32_e32 v13, 0xbfb8aa3b, v13
	v_mul_f32_e32 v14, 0xbfb8aa3b, v14
	v_mul_f32_e32 v15, 0xbfb8aa3b, v15
	v_mul_f32_e32 v8, 0xbfb8aa3b, v8
	v_mul_f32_e32 v9, 0xbfb8aa3b, v9
	v_mul_f32_e32 v10, 0xbfb8aa3b, v10
	v_mul_f32_e32 v11, 0xbfb8aa3b, v11
	v_exp_f32_e32 v12, v12
	v_exp_f32_e32 v13, v13
	v_exp_f32_e32 v14, v14
	v_exp_f32_e32 v15, v15
	v_exp_f32_e32 v8, v8
	v_exp_f32_e32 v9, v9
	v_exp_f32_e32 v10, v10
	v_exp_f32_e32 v11, v11
	v_add_f32_e32 v12, 1.0, v12
	v_add_f32_e32 v13, 1.0, v13
	v_add_f32_e32 v14, 1.0, v14
	v_add_f32_e32 v15, 1.0, v15
	v_add_f32_e32 v8, 1.0, v8
	v_add_f32_e32 v9, 1.0, v9
	v_add_f32_e32 v10, 1.0, v10
	v_add_f32_e32 v11, 1.0, v11
	v_rcp_f32_e32 v12, v12
	v_rcp_f32_e32 v13, v13
	v_rcp_f32_e32 v14, v14
	v_rcp_f32_e32 v15, v15
	v_rcp_f32_e32 v8, v8
	v_rcp_f32_e32 v9, v9
	v_rcp_f32_e32 v10, v10
	v_rcp_f32_e32 v11, v11
	s_nop 0
	s_waitcnt vmcnt(14)
	v_fma_f32 v222, v124, v112, v222
	v_fma_f32 v223, v125, v113, v223
	v_fma_f32 v224, v126, v114, v224
	v_fma_f32 v225, v127, v115, v225
	v_fma_f32 v218, v120, v116, v218
	v_fma_f32 v219, v121, v117, v219
	v_fma_f32 v220, v122, v118, v220
	v_fma_f32 v221, v123, v119, v221
	v_mul_f32_e32 v124, v222, v222
	v_mul_f32_e32 v125, v224, v224
	v_mul_f32_e32 v126, v218, v218
	v_mul_f32_e32 v127, v220, v220
	v_fmac_f32_e32 v124, v223, v223
	v_fmac_f32_e32 v125, v225, v225
	v_fmac_f32_e32 v126, v219, v219
	v_fmac_f32_e32 v127, v221, v221
	v_cvt_pk_bf16_f32 v112, v222, v223
	v_cvt_pk_bf16_f32 v113, v224, v225
	v_cvt_pk_bf16_f32 v114, v218, v219
	v_cvt_pk_bf16_f32 v115, v220, v221
	v_add_f32_e32 v124, v124, v125
	v_add_f32_e32 v126, v126, v127
	v_add_f32_e32 v194, v124, v126
	global_store_dwordx4 v191, v[112:115], s[20:21]
	v_mov_b32_e32 v202, v194
	s_nop 0
	s_nop 0
	v_permlane16_swap_b32_e32 v194, v202
	v_add_f32_e32 v194, v194, v202
	v_mov_b32_e32 v202, v194
	s_nop 1
	v_permlane32_swap_b32_e32 v194, v202
	v_add_f32_e32 v194, v194, v202
	s_and_b64 exec, exec, s[4:5]
	global_atomic_add_f32 v192, v194, s[60:61]
	s_mov_b64 exec, s[0:1]
	s_waitcnt vmcnt(14)
	v_fma_f32 v180, v108, v100, v180
	v_fma_f32 v181, v109, v101, v181
	v_fma_f32 v182, v110, v102, v182
	v_fma_f32 v183, v111, v103, v183
	v_fma_f32 v176, v104, v96, v176
	v_fma_f32 v177, v105, v97, v177
	v_fma_f32 v178, v106, v98, v178
	v_fma_f32 v179, v107, v99, v179
	v_mul_f32_e32 v108, v180, v180
	v_mul_f32_e32 v109, v182, v182
	v_mul_f32_e32 v110, v176, v176
	v_mul_f32_e32 v111, v178, v178
	v_fmac_f32_e32 v108, v181, v181
	v_fmac_f32_e32 v109, v183, v183
	v_fmac_f32_e32 v110, v177, v177
	v_fmac_f32_e32 v111, v179, v179
	v_cvt_pk_bf16_f32 v100, v180, v181
	v_cvt_pk_bf16_f32 v101, v182, v183
	v_cvt_pk_bf16_f32 v102, v176, v177
	v_cvt_pk_bf16_f32 v103, v178, v179
	v_add_f32_e32 v108, v108, v109
	v_add_f32_e32 v110, v110, v111
	v_add_u32_e32 v193, 0x8000, v191
	v_add_f32_e32 v195, v108, v110
	global_store_dwordx4 v193, v[100:103], s[20:21]
	v_mov_b32_e32 v203, v195
	v_add_u32_e32 v193, 0x40, v192
	s_nop 0
	v_permlane16_swap_b32_e32 v195, v203
	v_add_f32_e32 v195, v195, v203
	v_mov_b32_e32 v203, v195
	s_nop 1
	v_permlane32_swap_b32_e32 v195, v203
	v_add_f32_e32 v195, v195, v203
	s_and_b64 exec, exec, s[4:5]
	global_atomic_add_f32 v193, v195, s[60:61]
	s_mov_b64 exec, s[0:1]
	s_waitcnt vmcnt(14)
; __device__ __forceinline__ unsigned cvt_pk_bf16(float lo, float hi) { unsigned r; asm volatile("v_cvt_pk_bf16_f32 %0, %1, %2" : "=v"(r) : "v"(lo), "v"(hi)); return r; }
; __device__ __forceinline__ float fast_sigmoid(float x) { return __builtin_amdgcn_rcpf(1.0f + __builtin_amdgcn_exp2f(x * -1.44269504f)); }
;     __device__ __forceinline__ void operator()(const Acc& acc, const Unit& u, int wr, int wc, int fr, int fq, LAS unsigned char* lds, f32x4 epar) const {
;     ...
;         for (int ai = 0; ai < 2; ++ai)
; #pragma unroll
;             for (int m = 0; m < 4; ++m) { const int r = u.pm * BM + ai * HALF + wr * 64 + m * 16 + fr; const size_t off = (size_t)r * DM + c0;
;                 f32x4 v0 = xv[ai][m][0], v1 = xv[ai][m][1];
;                 const f32x4 za0 = acc[ai][0][m][0], za1 = acc[ai][0][m][1], zg0 = acc[ai][1][m][0], zg1 = acc[ai][1][m][1];
; #pragma unroll
;                 for (int j = 0; j < 4; ++j) { v0[j] += za0[j] * fast_sigmoid(zg0[j]); v1[j] += za1[j] * fast_sigmoid(zg1[j]); }
;                 u32x4 w; w.x = cvt_pk_bf16(v0[0], v0[1]); w.y = cvt_pk_bf16(v0[2], v0[3]); w.z = cvt_pk_bf16(v1[0], v1[1]); w.w = cvt_pk_bf16(v1[2], v1[3]);
;                 *(u32x4*)(HB + off) = w;
;                 float s = (v0[0] * v0[0] + v0[1] * v0[1]) + (v0[2] * v0[2] + v0[3] * v0[3]) + (v1[0] * v1[0] + v1[1] * v1[1]) + (v1[2] * v1[2] + v1[3] * v1[3]);
;                 s += __shfl_xor(s, 16); s += __shfl_xor(s, 32);
;                 if (fq == 0) unsafeAtomicAdd(ssq + r, s); }
	v_fma_f32 v172, v92, v84, v172
	v_fma_f32 v173, v93, v85, v173
	v_fma_f32 v174, v94, v86, v174
	v_fma_f32 v175, v95, v87, v175
	v_fma_f32 v168, v88, v80, v168
	v_fma_f32 v169, v89, v81, v169
	v_fma_f32 v170, v90, v82, v170
	v_fma_f32 v171, v91, v83, v171
	v_mul_f32_e32 v92, v172, v172
	v_mul_f32_e32 v93, v174, v174
	v_mul_f32_e32 v94, v168, v168
	v_mul_f32_e32 v95, v170, v170
	v_fmac_f32_e32 v92, v173, v173
	v_fmac_f32_e32 v93, v175, v175
	v_fmac_f32_e32 v94, v169, v169
	v_fmac_f32_e32 v95, v171, v171
	v_cvt_pk_bf16_f32 v84, v172, v173
	v_cvt_pk_bf16_f32 v85, v174, v175
	v_cvt_pk_bf16_f32 v86, v168, v169
	v_cvt_pk_bf16_f32 v87, v170, v171
	v_add_f32_e32 v92, v92, v93
	v_add_f32_e32 v94, v94, v95
	v_add_u32_e32 v193, 0x10000, v191
	v_add_f32_e32 v196, v92, v94
	global_store_dwordx4 v193, v[84:87], s[20:21]
	v_mov_b32_e32 v204, v196
	v_add_u32_e32 v193, 0x80, v192
	s_nop 0
	v_permlane16_swap_b32_e32 v196, v204
	v_add_f32_e32 v196, v196, v204
	v_mov_b32_e32 v204, v196
	s_nop 1
	v_permlane32_swap_b32_e32 v196, v204
	v_add_f32_e32 v196, v196, v204
	s_and_b64 exec, exec, s[4:5]
	global_atomic_add_f32 v193, v196, s[60:61]
	s_mov_b64 exec, s[0:1]
	s_waitcnt vmcnt(14)
	v_fma_f32 v164, v76, v68, v164
	v_fma_f32 v165, v77, v69, v165
	v_fma_f32 v166, v78, v70, v166
	v_fma_f32 v167, v79, v71, v167
	v_fma_f32 v160, v72, v64, v160
	v_fma_f32 v161, v73, v65, v161
	v_fma_f32 v162, v74, v66, v162
	v_fma_f32 v163, v75, v67, v163
	v_mul_f32_e32 v76, v164, v164
	v_mul_f32_e32 v77, v166, v166
	v_mul_f32_e32 v78, v160, v160
	v_mul_f32_e32 v79, v162, v162
	v_fmac_f32_e32 v76, v165, v165
	v_fmac_f32_e32 v77, v167, v167
	v_fmac_f32_e32 v78, v161, v161
	v_fmac_f32_e32 v79, v163, v163
	v_cvt_pk_bf16_f32 v68, v164, v165
	v_cvt_pk_bf16_f32 v69, v166, v167
	v_cvt_pk_bf16_f32 v70, v160, v161
	v_cvt_pk_bf16_f32 v71, v162, v163
	v_add_f32_e32 v76, v76, v77
	v_add_f32_e32 v78, v78, v79
	v_add_u32_e32 v193, 0x18000, v191
	v_add_f32_e32 v197, v76, v78
	global_store_dwordx4 v193, v[68:71], s[20:21]
	v_mov_b32_e32 v205, v197
	v_add_u32_e32 v193, 0xc0, v192
	s_nop 0
	v_permlane16_swap_b32_e32 v197, v205
	v_add_f32_e32 v197, v197, v205
	v_mov_b32_e32 v205, v197
	s_nop 1
	v_permlane32_swap_b32_e32 v197, v205
	v_add_f32_e32 v197, v197, v205
	s_and_b64 exec, exec, s[4:5]
	global_atomic_add_f32 v193, v197, s[60:61]
	s_mov_b64 exec, s[0:1]
	s_waitcnt vmcnt(14)
	v_fma_f32 v156, v60, v52, v156
	v_fma_f32 v157, v61, v53, v157
	v_fma_f32 v158, v62, v54, v158
	v_fma_f32 v159, v63, v55, v159
	v_fma_f32 v152, v56, v48, v152
	v_fma_f32 v153, v57, v49, v153
	v_fma_f32 v154, v58, v50, v154
	v_fma_f32 v155, v59, v51, v155
	v_mul_f32_e32 v60, v156, v156
	v_mul_f32_e32 v61, v158, v158
	v_mul_f32_e32 v62, v152, v152
	v_mul_f32_e32 v63, v154, v154
	v_fmac_f32_e32 v60, v157, v157
	v_fmac_f32_e32 v61, v159, v159
	v_fmac_f32_e32 v62, v153, v153
	v_fmac_f32_e32 v63, v155, v155
	v_cvt_pk_bf16_f32 v52, v156, v157
	v_cvt_pk_bf16_f32 v53, v158, v159
	v_cvt_pk_bf16_f32 v54, v152, v153
	v_cvt_pk_bf16_f32 v55, v154, v155
	v_add_f32_e32 v60, v60, v61
	v_add_f32_e32 v62, v62, v63
	v_add_u32_e32 v193, 0x40000, v191
	v_add_f32_e32 v198, v60, v62
	global_store_dwordx4 v193, v[52:55], s[20:21]
	v_mov_b32_e32 v124, v198
	v_add_u32_e32 v193, 0x200, v192
	s_nop 0
	v_permlane16_swap_b32_e32 v198, v124
	v_add_f32_e32 v198, v198, v124
	v_mov_b32_e32 v124, v198
	s_nop 1
	v_permlane32_swap_b32_e32 v198, v124
	v_add_f32_e32 v198, v198, v124
	s_and_b64 exec, exec, s[4:5]
	global_atomic_add_f32 v193, v198, s[60:61]
	s_mov_b64 exec, s[0:1]
	s_waitcnt vmcnt(14)
; __device__ __forceinline__ unsigned cvt_pk_bf16(float lo, float hi) { unsigned r; asm volatile("v_cvt_pk_bf16_f32 %0, %1, %2" : "=v"(r) : "v"(lo), "v"(hi)); return r; }
; __device__ __forceinline__ float fast_sigmoid(float x) { return __builtin_amdgcn_rcpf(1.0f + __builtin_amdgcn_exp2f(x * -1.44269504f)); }
;     __device__ __forceinline__ void operator()(const Acc& acc, const Unit& u, int wr, int wc, int fr, int fq, LAS unsigned char* lds, f32x4 epar) const {
;     ...
;         for (int ai = 0; ai < 2; ++ai)
; #pragma unroll
;             for (int m = 0; m < 4; ++m) { const int r = u.pm * BM + ai * HALF + wr * 64 + m * 16 + fr; const size_t off = (size_t)r * DM + c0;
;                 f32x4 v0 = xv[ai][m][0], v1 = xv[ai][m][1];
;                 const f32x4 za0 = acc[ai][0][m][0], za1 = acc[ai][0][m][1], zg0 = acc[ai][1][m][0], zg1 = acc[ai][1][m][1];
; #pragma unroll
;                 for (int j = 0; j < 4; ++j) { v0[j] += za0[j] * fast_sigmoid(zg0[j]); v1[j] += za1[j] * fast_sigmoid(zg1[j]); }
;                 u32x4 w; w.x = cvt_pk_bf16(v0[0], v0[1]); w.y = cvt_pk_bf16(v0[2], v0[3]); w.z = cvt_pk_bf16(v1[0], v1[1]); w.w = cvt_pk_bf16(v1[2], v1[3]);
;                 *(u32x4*)(HB + off) = w;
;                 float s = (v0[0] * v0[0] + v0[1] * v0[1]) + (v0[2] * v0[2] + v0[3] * v0[3]) + (v1[0] * v1[0] + v1[1] * v1[1]) + (v1[2] * v1[2] + v1[3] * v1[3]);
;                 s += __shfl_xor(s, 16); s += __shfl_xor(s, 32);
;                 if (fq == 0) unsafeAtomicAdd(ssq + r, s); }
	v_fma_f32 v148, v44, v36, v148
	v_fma_f32 v149, v45, v37, v149
	v_fma_f32 v150, v46, v38, v150
	v_fma_f32 v151, v47, v39, v151
	v_fma_f32 v144, v40, v32, v144
	v_fma_f32 v145, v41, v33, v145
	v_fma_f32 v146, v42, v34, v146
	v_fma_f32 v147, v43, v35, v147
	v_mul_f32_e32 v44, v148, v148
	v_mul_f32_e32 v45, v150, v150
	v_mul_f32_e32 v46, v144, v144
	v_mul_f32_e32 v47, v146, v146
	v_fmac_f32_e32 v44, v149, v149
	v_fmac_f32_e32 v45, v151, v151
	v_fmac_f32_e32 v46, v145, v145
	v_fmac_f32_e32 v47, v147, v147
	v_cvt_pk_bf16_f32 v36, v148, v149
	v_cvt_pk_bf16_f32 v37, v150, v151
	v_cvt_pk_bf16_f32 v38, v144, v145
	v_cvt_pk_bf16_f32 v39, v146, v147
	v_add_f32_e32 v44, v44, v45
	v_add_f32_e32 v46, v46, v47
	v_add_u32_e32 v193, 0x48000, v191
	v_add_f32_e32 v199, v44, v46
	global_store_dwordx4 v193, v[36:39], s[20:21]
	v_mov_b32_e32 v125, v199
	v_add_u32_e32 v193, 0x240, v192
	s_nop 0
	v_permlane16_swap_b32_e32 v199, v125
	v_add_f32_e32 v199, v199, v125
	v_mov_b32_e32 v125, v199
	s_nop 1
	v_permlane32_swap_b32_e32 v199, v125
	v_add_f32_e32 v199, v199, v125
	s_and_b64 exec, exec, s[4:5]
	global_atomic_add_f32 v193, v199, s[60:61]
	s_mov_b64 exec, s[0:1]
	s_waitcnt vmcnt(14)
	v_fma_f32 v140, v28, v20, v140
	v_fma_f32 v141, v29, v21, v141
	v_fma_f32 v142, v30, v22, v142
	v_fma_f32 v143, v31, v23, v143
	v_fma_f32 v136, v24, v16, v136
	v_fma_f32 v137, v25, v17, v137
	v_fma_f32 v138, v26, v18, v138
	v_fma_f32 v139, v27, v19, v139
	v_mul_f32_e32 v28, v140, v140
	v_mul_f32_e32 v29, v142, v142
	v_mul_f32_e32 v30, v136, v136
	v_mul_f32_e32 v31, v138, v138
	v_fmac_f32_e32 v28, v141, v141
	v_fmac_f32_e32 v29, v143, v143
	v_fmac_f32_e32 v30, v137, v137
	v_fmac_f32_e32 v31, v139, v139
	v_cvt_pk_bf16_f32 v20, v140, v141
	v_cvt_pk_bf16_f32 v21, v142, v143
	v_cvt_pk_bf16_f32 v22, v136, v137
	v_cvt_pk_bf16_f32 v23, v138, v139
	v_add_f32_e32 v28, v28, v29
	v_add_f32_e32 v30, v30, v31
	v_add_u32_e32 v193, 0x50000, v191
	v_add_f32_e32 v200, v28, v30
	global_store_dwordx4 v193, v[20:23], s[20:21]
	v_mov_b32_e32 v126, v200
	v_add_u32_e32 v193, 0x280, v192
	s_nop 0
	v_permlane16_swap_b32_e32 v200, v126
	v_add_f32_e32 v200, v200, v126
	v_mov_b32_e32 v126, v200
	s_nop 1
	v_permlane32_swap_b32_e32 v200, v126
	v_add_f32_e32 v200, v200, v126
	s_and_b64 exec, exec, s[4:5]
	global_atomic_add_f32 v193, v200, s[60:61]
	s_mov_b64 exec, s[0:1]
	s_waitcnt vmcnt(14)
	v_fma_f32 v132, v12, v4, v132
	v_fma_f32 v133, v13, v5, v133
	v_fma_f32 v134, v14, v6, v134
	v_fma_f32 v135, v15, v7, v135
	v_fma_f32 v128, v8, v0, v128
	v_fma_f32 v129, v9, v1, v129
	v_fma_f32 v130, v10, v2, v130
	v_fma_f32 v131, v11, v3, v131
	v_mul_f32_e32 v12, v132, v132
	v_mul_f32_e32 v13, v134, v134
	v_mul_f32_e32 v14, v128, v128
	v_mul_f32_e32 v15, v130, v130
	v_fmac_f32_e32 v12, v133, v133
	v_fmac_f32_e32 v13, v135, v135
	v_fmac_f32_e32 v14, v129, v129
	v_fmac_f32_e32 v15, v131, v131
	v_cvt_pk_bf16_f32 v4, v132, v133
	v_cvt_pk_bf16_f32 v5, v134, v135
	v_cvt_pk_bf16_f32 v6, v128, v129
	v_cvt_pk_bf16_f32 v7, v130, v131
	v_add_f32_e32 v12, v12, v13
	v_add_f32_e32 v14, v14, v15
	v_add_u32_e32 v193, 0x58000, v191
	v_add_f32_e32 v201, v12, v14
	global_store_dwordx4 v193, v[4:7], s[20:21]
	v_mov_b32_e32 v127, v201
	v_add_u32_e32 v193, 0x2c0, v192
	s_nop 0
	v_permlane16_swap_b32_e32 v201, v127
	v_add_f32_e32 v201, v201, v127
	v_mov_b32_e32 v127, v201
	s_nop 1
	v_permlane32_swap_b32_e32 v201, v127
	v_add_f32_e32 v201, v201, v127
	s_and_b64 exec, exec, s[4:5]
	global_atomic_add_f32 v193, v201, s[60:61]
	s_mov_b64 exec, s[0:1]
	s_branch .LBB0_618

; __global__ void __launch_bounds__(512, 2) fwd_megakernel(Params p) {
	.amdhsa_kernel _Z14fwd_megakernel6Params
		.amdhsa_group_segment_fixed_size 0
		.amdhsa_private_segment_fixed_size 0
		.amdhsa_kernarg_size 432
		.amdhsa_user_sgpr_count 2
		.amdhsa_user_sgpr_dispatch_ptr 0
		.amdhsa_user_sgpr_queue_ptr 0
		.amdhsa_user_sgpr_kernarg_segment_ptr 1
		.amdhsa_user_sgpr_dispatch_id 0
		.amdhsa_user_sgpr_kernarg_preload_length 0
		.amdhsa_user_sgpr_kernarg_preload_offset 0
		.amdhsa_user_sgpr_private_segment_size 0
		.amdhsa_uses_dynamic_stack 0
		.amdhsa_enable_private_segment 0
		.amdhsa_system_sgpr_workgroup_id_x 1
		.amdhsa_system_sgpr_workgroup_id_y 0
		.amdhsa_system_sgpr_workgroup_id_z 0
		.amdhsa_system_sgpr_workgroup_info 0
		.amdhsa_system_vgpr_workitem_id 2
		.amdhsa_next_free_vgpr 253
		.amdhsa_next_free_sgpr 100
		.amdhsa_accum_offset 256
		.amdhsa_reserve_vcc 1
		.amdhsa_float_round_mode_32 0
		.amdhsa_float_round_mode_16_64 0
		.amdhsa_float_denorm_mode_32 3
		.amdhsa_float_denorm_mode_16_64 3
		.amdhsa_dx10_clamp 1
		.amdhsa_ieee_mode 1
		.amdhsa_fp16_overflow 0
		.amdhsa_tg_split 0
		.amdhsa_exception_fp_ieee_invalid_op 0
		.amdhsa_exception_fp_denorm_src 0
		.amdhsa_exception_fp_ieee_div_zero 0
		.amdhsa_exception_fp_ieee_overflow 0
		.amdhsa_exception_fp_ieee_underflow 0
		.amdhsa_exception_fp_ieee_inexact 0
		.amdhsa_exception_int_div_zero 0
	.end_amdhsa_kernel

; __global__ void __launch_bounds__(512, 2) fwd_megakernel(Params p) {
amdhsa.kernels:
  - .agpr_count:     0
    .args:
      - .offset:         0
        .size:           176
        .value_kind:     by_value
      - .offset:         176
        .size:           4
        .value_kind:     hidden_block_count_x
      - .offset:         180
        .size:           4
        .value_kind:     hidden_block_count_y
      - .offset:         184
        .size:           4
        .value_kind:     hidden_block_count_z
      - .offset:         188
        .size:           2
        .value_kind:     hidden_group_size_x
      - .offset:         190
        .size:           2
        .value_kind:     hidden_group_size_y
      - .offset:         192
        .size:           2
        .value_kind:     hidden_group_size_z
      - .offset:         194
        .size:           2
        .value_kind:     hidden_remainder_x
      - .offset:         196
        .size:           2
        .value_kind:     hidden_remainder_y
      - .offset:         198
        .size:           2
        .value_kind:     hidden_remainder_z
      - .offset:         216
        .size:           8
        .value_kind:     hidden_global_offset_x
      - .offset:         224
        .size:           8
        .value_kind:     hidden_global_offset_y
      - .offset:         232
        .size:           8
        .value_kind:     hidden_global_offset_z
      - .offset:         240
        .size:           2
        .value_kind:     hidden_grid_dims
      - .offset:         264
        .size:           8
        .value_kind:     hidden_multigrid_sync_arg
      - .offset:         296
        .size:           4
        .value_kind:     hidden_dynamic_lds_size
    .group_segment_fixed_size: 0
    .kernarg_segment_align: 8
    .kernarg_segment_size: 432
    .language:       OpenCL C
    .language_version:
      - 2
      - 0
    .max_flat_workgroup_size: 512
    .name:           _Z14fwd_megakernel6Params
    .private_segment_fixed_size: 0
    .sgpr_count:     106
    .sgpr_spill_count: 56
    .symbol:         _Z14fwd_megakernel6Params.kd
    .uniform_work_group_size: 1
    .uses_dynamic_stack: false
    .vgpr_count:     253
    .vgpr_spill_count: 0
    .wavefront_size: 64
